# FF1 GEMMs (both layers): one static s_setprio 1 for the lagging wave half (waves 4-7) per tile, reset at the epilogue; other GEMMs without priority toggling
# speedup vs baseline: 1.0062x; 1.0010x over previous
.LBB0_1651:
	s_setprio 0
	s_or_b64 exec, exec, s[60:61]
	v_and_b32_e32 v134, 64, v165
	v_xor_b32_e32 v132, 16, v165
	v_add_u32_e32 v134, 64, v134
	v_max_f32_e32 v124, v124, v124
	v_max_f32_e32 v125, v125, v125
	v_and_b32_e32 v128, 16, v128
	v_lshlrev_b32_e32 v133, 2, v155
	v_cmp_lt_i32_e32 vcc, v132, v134
	v_max_f32_e32 v124, 0, v124
	v_max_f32_e32 v125, 0, v125
	v_max_f32_e32 v126, v126, v126
	v_max_f32_e32 v127, v127, v127
	v_max_f32_e32 v120, v120, v120
	v_max_f32_e32 v121, v121, v121
	v_cndmask_b32_e32 v132, v165, v132, vcc
	v_add_u32_e32 v134, 12, v133
	v_cmp_eq_u32_e32 vcc, 0, v128
	v_max_f32_e32 v126, 0, v126
	v_max_f32_e32 v127, 0, v127
	v_pk_mul_f32 v[124:125], v[124:125], v[124:125]
	v_max_f32_e32 v120, 0, v120
	v_max_f32_e32 v121, 0, v121
	v_max_f32_e32 v122, v122, v122
	v_max_f32_e32 v123, v123, v123
	v_cndmask_b32_e32 v128, v134, v133, vcc
	v_cvt_pk_bf16_f32 v133, v124, v125
	v_pk_mul_f32 v[124:125], v[126:127], v[126:127]
	v_max_f32_e32 v122, 0, v122
	v_max_f32_e32 v123, 0, v123
	v_pk_mul_f32 v[120:121], v[120:121], v[120:121]
	v_cvt_pk_bf16_f32 v126, v124, v125
	v_cvt_pk_bf16_f32 v124, v120, v121
	v_pk_mul_f32 v[120:121], v[122:123], v[122:123]
	v_lshlrev_b32_e32 v132, 2, v132
	v_cvt_pk_bf16_f32 v122, v120, v121
	v_cndmask_b32_e32 v120, v126, v122, vcc
	v_cndmask_b32_e32 v121, v133, v124, vcc
	ds_bpermute_b32 v123, v132, v120
	ds_bpermute_b32 v127, v132, v121
	s_lshl_b32 s1, s71, 8
	v_or_b32_e32 v130, s36, v156
	v_lshlrev_b32_e32 v131, 5, v154
	v_max_f32_e32 v116, v116, v116
	v_max_f32_e32 v117, v117, v117
	v_max_f32_e32 v112, v112, v112
	v_max_f32_e32 v113, v113, v113
	v_add_u32_e32 v130, v130, v157
	v_or3_b32 v120, v131, s1, v128
	v_max_f32_e32 v116, 0, v116
	v_max_f32_e32 v117, 0, v117
	v_max_f32_e32 v118, v118, v118
	v_max_f32_e32 v119, v119, v119
	v_max_f32_e32 v112, 0, v112
	v_max_f32_e32 v113, 0, v113
	v_max_f32_e32 v114, v114, v114
	v_max_f32_e32 v115, v115, v115
	v_lshlrev_b32_e32 v128, 1, v120
	v_ashrrev_i32_e32 v131, 31, v130
	v_max_f32_e32 v118, 0, v118
	v_max_f32_e32 v119, 0, v119
	v_pk_mul_f32 v[116:117], v[116:117], v[116:117]
	v_max_f32_e32 v114, 0, v114
	v_max_f32_e32 v115, 0, v115
	v_pk_mul_f32 v[112:113], v[112:113], v[112:113]
	v_max_f32_e32 v108, v108, v108
	v_max_f32_e32 v109, v109, v109
	v_max_f32_e32 v104, v104, v104
	v_max_f32_e32 v105, v105, v105
	v_lshl_add_u64 v[120:121], s[4:5], 0, v[128:129]
	s_waitcnt lgkmcnt(0)
	v_cndmask_b32_e32 v125, v122, v123, vcc
	v_cndmask_b32_e32 v124, v124, v127, vcc
	v_cndmask_b32_e32 v123, v123, v126, vcc
	v_cndmask_b32_e32 v122, v127, v133, vcc
	v_lshlrev_b64 v[126:127], 13, v[130:131]
	v_cvt_pk_bf16_f32 v128, v116, v117
	v_pk_mul_f32 v[116:117], v[118:119], v[118:119]
	v_cvt_pk_bf16_f32 v131, v112, v113
	v_pk_mul_f32 v[112:113], v[114:115], v[114:115]
	v_max_f32_e32 v108, 0, v108
	v_max_f32_e32 v109, 0, v109
	v_max_f32_e32 v110, v110, v110
	v_max_f32_e32 v111, v111, v111
	v_max_f32_e32 v104, 0, v104
	v_max_f32_e32 v105, 0, v105
	v_max_f32_e32 v106, v106, v106
	v_max_f32_e32 v107, v107, v107
	v_cvt_pk_bf16_f32 v119, v116, v117
	v_cvt_pk_bf16_f32 v112, v112, v113
	v_lshl_add_u64 v[116:117], v[120:121], 0, v[126:127]
	v_max_f32_e32 v110, 0, v110
	v_max_f32_e32 v111, 0, v111
	v_pk_mul_f32 v[108:109], v[108:109], v[108:109]
	v_max_f32_e32 v106, 0, v106
	v_max_f32_e32 v107, 0, v107
	v_pk_mul_f32 v[104:105], v[104:105], v[104:105]
	v_cndmask_b32_e32 v113, v119, v112, vcc
	global_store_dwordx4 v[116:117], v[122:125], off
	ds_bpermute_b32 v113, v132, v113
	v_cndmask_b32_e32 v114, v128, v131, vcc
	v_cvt_pk_bf16_f32 v122, v108, v109
	v_pk_mul_f32 v[108:109], v[110:111], v[110:111]
	v_cvt_pk_bf16_f32 v123, v104, v105
	v_pk_mul_f32 v[104:105], v[106:107], v[106:107]
	v_cvt_pk_bf16_f32 v111, v108, v109
	v_cvt_pk_bf16_f32 v104, v104, v105
	v_cndmask_b32_e32 v105, v111, v104, vcc
	ds_bpermute_b32 v133, v132, v114
	ds_bpermute_b32 v105, v132, v105
	v_cndmask_b32_e32 v106, v122, v123, vcc
	v_or_b32_e32 v118, 16, v130
	ds_bpermute_b32 v124, v132, v106
	s_waitcnt lgkmcnt(0)
	v_cndmask_b32_e32 v115, v112, v113, vcc
	v_cndmask_b32_e32 v113, v113, v119, vcc
	v_ashrrev_i32_e32 v119, 31, v118
	v_max_f32_e32 v100, v100, v100
	v_max_f32_e32 v101, v101, v101
	v_max_f32_e32 v96, v96, v96
	v_max_f32_e32 v97, v97, v97
	v_lshlrev_b64 v[118:119], 13, v[118:119]
	v_or_b32_e32 v110, 32, v130
	v_max_f32_e32 v100, 0, v100
	v_max_f32_e32 v101, 0, v101
	v_max_f32_e32 v102, v102, v102
	v_max_f32_e32 v103, v103, v103
	v_max_f32_e32 v96, 0, v96
	v_max_f32_e32 v97, 0, v97
	v_max_f32_e32 v98, v98, v98
	v_max_f32_e32 v99, v99, v99
	v_cndmask_b32_e32 v114, v131, v133, vcc
	v_cndmask_b32_e32 v112, v133, v128, vcc
	v_lshl_add_u64 v[108:109], v[120:121], 0, v[118:119]
	v_cndmask_b32_e32 v107, v104, v105, vcc
	v_cndmask_b32_e32 v105, v105, v111, vcc
	v_ashrrev_i32_e32 v111, 31, v110
	v_max_f32_e32 v102, 0, v102
	v_max_f32_e32 v103, 0, v103
	v_pk_mul_f32 v[100:101], v[100:101], v[100:101]
	v_max_f32_e32 v98, 0, v98
	v_max_f32_e32 v99, 0, v99
	v_pk_mul_f32 v[96:97], v[96:97], v[96:97]
	v_max_f32_e32 v92, v92, v92
	v_max_f32_e32 v93, v93, v93
	global_store_dwordx4 v[108:109], v[112:115], off
	v_lshlrev_b64 v[110:111], 13, v[110:111]
	v_max_f32_e32 v92, 0, v92
	v_cvt_pk_bf16_f32 v112, v100, v101
	v_pk_mul_f32 v[100:101], v[102:103], v[102:103]
	v_cvt_pk_bf16_f32 v113, v96, v97
	v_pk_mul_f32 v[96:97], v[98:99], v[98:99]
	v_max_f32_e32 v93, 0, v93
	v_max_f32_e32 v94, v94, v94
	v_max_f32_e32 v95, v95, v95
	v_max_f32_e32 v88, v88, v88
	v_max_f32_e32 v89, v89, v89
	v_cndmask_b32_e32 v106, v123, v124, vcc
	v_cndmask_b32_e32 v104, v124, v122, vcc
	v_cvt_pk_bf16_f32 v103, v100, v101
	v_cvt_pk_bf16_f32 v96, v96, v97
	v_lshl_add_u64 v[100:101], v[120:121], 0, v[110:111]
	v_max_f32_e32 v94, 0, v94
	v_max_f32_e32 v95, 0, v95
	v_pk_mul_f32 v[92:93], v[92:93], v[92:93]
	v_max_f32_e32 v88, 0, v88
	v_max_f32_e32 v89, 0, v89
	v_max_f32_e32 v90, v90, v90
	v_max_f32_e32 v91, v91, v91
	v_cndmask_b32_e32 v97, v103, v96, vcc
	global_store_dwordx4 v[100:101], v[104:107], off
	v_max_f32_e32 v90, 0, v90
	v_max_f32_e32 v91, 0, v91
	v_cvt_pk_bf16_f32 v104, v92, v93
	v_pk_mul_f32 v[92:93], v[94:95], v[94:95]
	v_pk_mul_f32 v[88:89], v[88:89], v[88:89]
	ds_bpermute_b32 v97, v132, v97
	v_cvt_pk_bf16_f32 v92, v92, v93
	v_cvt_pk_bf16_f32 v93, v88, v89
	v_pk_mul_f32 v[88:89], v[90:91], v[90:91]
	v_or_b32_e32 v102, 48, v130
	v_cvt_pk_bf16_f32 v94, v88, v89
	v_cndmask_b32_e32 v89, v104, v93, vcc
	ds_bpermute_b32 v105, v132, v89
	v_max_f32_e32 v84, v84, v84
	v_max_f32_e32 v85, v85, v85
	s_waitcnt lgkmcnt(0)
	v_cndmask_b32_e32 v99, v96, v97, vcc
	v_cndmask_b32_e32 v97, v97, v103, vcc
	v_ashrrev_i32_e32 v103, 31, v102
	v_cndmask_b32_e32 v88, v92, v94, vcc
	v_max_f32_e32 v84, 0, v84
	v_max_f32_e32 v85, 0, v85
	v_max_f32_e32 v86, v86, v86
	v_max_f32_e32 v87, v87, v87
	v_max_f32_e32 v80, v80, v80
	v_max_f32_e32 v81, v81, v81
	ds_bpermute_b32 v95, v132, v88
	v_lshlrev_b64 v[88:89], 13, v[102:103]
	v_max_f32_e32 v86, 0, v86
	v_max_f32_e32 v87, 0, v87
	v_pk_mul_f32 v[84:85], v[84:85], v[84:85]
	v_max_f32_e32 v80, 0, v80
	v_max_f32_e32 v81, 0, v81
	v_max_f32_e32 v82, v82, v82
	v_max_f32_e32 v83, v83, v83
	v_lshl_add_u64 v[90:91], v[120:121], 0, v[88:89]
	v_cndmask_b32_e32 v88, v93, v105, vcc
	v_cvt_pk_bf16_f32 v93, v84, v85
	v_pk_mul_f32 v[84:85], v[86:87], v[86:87]
	v_max_f32_e32 v82, 0, v82
	v_max_f32_e32 v83, 0, v83
	v_pk_mul_f32 v[80:81], v[80:81], v[80:81]
	v_cvt_pk_bf16_f32 v84, v84, v85
	v_cvt_pk_bf16_f32 v85, v80, v81
	v_pk_mul_f32 v[80:81], v[82:83], v[82:83]
	v_cndmask_b32_e32 v82, v93, v85, vcc
	v_cvt_pk_bf16_f32 v80, v80, v81
	v_cndmask_b32_e32 v81, v84, v80, vcc
	ds_bpermute_b32 v83, v132, v81
	ds_bpermute_b32 v82, v132, v82
	v_max_f32_e32 v76, v76, v76
	v_max_f32_e32 v77, v77, v77
	v_max_f32_e32 v76, 0, v76
	v_max_f32_e32 v77, 0, v77
	v_max_f32_e32 v78, v78, v78
	v_max_f32_e32 v79, v79, v79
	v_max_f32_e32 v72, v72, v72
	v_max_f32_e32 v73, v73, v73
	v_max_f32_e32 v78, 0, v78
	v_max_f32_e32 v79, 0, v79
	v_pk_mul_f32 v[76:77], v[76:77], v[76:77]
	v_max_f32_e32 v72, 0, v72
	v_max_f32_e32 v73, 0, v73
	v_max_f32_e32 v74, v74, v74
	v_max_f32_e32 v75, v75, v75
	s_waitcnt lgkmcnt(0)
	v_cndmask_b32_e32 v81, v80, v83, vcc
	v_cndmask_b32_e32 v80, v85, v82, vcc
	v_cvt_pk_bf16_f32 v85, v76, v77
	v_pk_mul_f32 v[76:77], v[78:79], v[78:79]
	v_max_f32_e32 v74, 0, v74
	v_max_f32_e32 v75, 0, v75
	v_pk_mul_f32 v[72:73], v[72:73], v[72:73]
	v_cvt_pk_bf16_f32 v76, v76, v77
	v_cvt_pk_bf16_f32 v77, v72, v73
	v_pk_mul_f32 v[72:73], v[74:75], v[74:75]
	v_cndmask_b32_e32 v74, v85, v77, vcc
	v_cvt_pk_bf16_f32 v72, v72, v73
	v_cndmask_b32_e32 v73, v76, v72, vcc
	ds_bpermute_b32 v75, v132, v73
	ds_bpermute_b32 v74, v132, v74
	v_max_f32_e32 v68, v68, v68
	v_max_f32_e32 v69, v69, v69
	v_max_f32_e32 v68, 0, v68
	v_max_f32_e32 v69, 0, v69
	v_max_f32_e32 v70, v70, v70
	v_max_f32_e32 v71, v71, v71
	v_max_f32_e32 v64, v64, v64
	v_max_f32_e32 v65, v65, v65
	v_max_f32_e32 v70, 0, v70
	v_max_f32_e32 v71, 0, v71
	v_pk_mul_f32 v[68:69], v[68:69], v[68:69]
	v_max_f32_e32 v64, 0, v64
	v_max_f32_e32 v65, 0, v65
	v_max_f32_e32 v66, v66, v66
	v_max_f32_e32 v67, v67, v67
	s_waitcnt lgkmcnt(0)
	v_cndmask_b32_e32 v73, v72, v75, vcc
	v_cndmask_b32_e32 v72, v77, v74, vcc
	v_cvt_pk_bf16_f32 v77, v68, v69
	v_pk_mul_f32 v[68:69], v[70:71], v[70:71]
	v_max_f32_e32 v66, 0, v66
	v_max_f32_e32 v67, 0, v67
	v_pk_mul_f32 v[64:65], v[64:65], v[64:65]
	v_cvt_pk_bf16_f32 v68, v68, v69
	v_cvt_pk_bf16_f32 v69, v64, v65
	v_pk_mul_f32 v[64:65], v[66:67], v[66:67]
	v_max_f32_e32 v60, v60, v60
	v_cvt_pk_bf16_f32 v64, v64, v65
	v_cndmask_b32_e32 v65, v68, v64, vcc
	ds_bpermute_b32 v65, v132, v65
	v_max_f32_e32 v61, v61, v61
	v_max_f32_e32 v56, v56, v56
	v_max_f32_e32 v57, v57, v57
	v_max_f32_e32 v60, 0, v60
	v_max_f32_e32 v61, 0, v61
	v_max_f32_e32 v62, v62, v62
	v_max_f32_e32 v63, v63, v63
	v_max_f32_e32 v56, 0, v56
	v_max_f32_e32 v57, 0, v57
	v_max_f32_e32 v58, v58, v58
	v_max_f32_e32 v59, v59, v59
	v_max_f32_e32 v62, 0, v62
	v_max_f32_e32 v63, 0, v63
	v_pk_mul_f32 v[60:61], v[60:61], v[60:61]
	v_max_f32_e32 v58, 0, v58
	v_max_f32_e32 v59, 0, v59
	v_pk_mul_f32 v[56:57], v[56:57], v[56:57]
	s_waitcnt lgkmcnt(0)
	v_cndmask_b32_e32 v67, v64, v65, vcc
	v_cndmask_b32_e32 v65, v65, v68, vcc
	v_cvt_pk_bf16_f32 v68, v60, v61
	v_pk_mul_f32 v[60:61], v[62:63], v[62:63]
	v_cvt_pk_bf16_f32 v62, v56, v57
	v_pk_mul_f32 v[56:57], v[58:59], v[58:59]
	v_cvt_pk_bf16_f32 v61, v60, v61
	v_cvt_pk_bf16_f32 v56, v56, v57
	v_cndmask_b32_e32 v57, v61, v56, vcc
	v_cndmask_b32_e32 v58, v68, v62, vcc
	ds_bpermute_b32 v57, v132, v57
	ds_bpermute_b32 v63, v132, v58
	v_max_f32_e32 v52, v52, v52
	v_max_f32_e32 v53, v53, v53
	v_max_f32_e32 v48, v48, v48
	v_max_f32_e32 v49, v49, v49
	v_cndmask_b32_e32 v79, v83, v84, vcc
	v_cndmask_b32_e32 v78, v82, v93, vcc
	v_cndmask_b32_e32 v66, v77, v69, vcc
	v_add_u32_e32 v60, 0x80, v130
	v_max_f32_e32 v52, 0, v52
	v_max_f32_e32 v53, 0, v53
	v_max_f32_e32 v54, v54, v54
	v_max_f32_e32 v55, v55, v55
	v_max_f32_e32 v48, 0, v48
	v_max_f32_e32 v49, 0, v49
	v_max_f32_e32 v50, v50, v50
	v_max_f32_e32 v51, v51, v51
	global_store_dwordx4 v[108:109], v[78:81], off offset:256
	ds_bpermute_b32 v78, v132, v66
	s_waitcnt lgkmcnt(0)
	v_cndmask_b32_e32 v59, v56, v57, vcc
	v_cndmask_b32_e32 v57, v57, v61, vcc
	v_ashrrev_i32_e32 v61, 31, v60
	v_max_f32_e32 v54, 0, v54
	v_max_f32_e32 v55, 0, v55
	v_pk_mul_f32 v[52:53], v[52:53], v[52:53]
	v_max_f32_e32 v50, 0, v50
	v_max_f32_e32 v51, 0, v51
	v_pk_mul_f32 v[48:49], v[48:49], v[48:49]
	v_max_f32_e32 v44, v44, v44
	v_max_f32_e32 v45, v45, v45
	v_max_f32_e32 v40, v40, v40
	v_max_f32_e32 v41, v41, v41
	v_cndmask_b32_e32 v58, v62, v63, vcc
	v_cndmask_b32_e32 v56, v63, v68, vcc
	v_lshlrev_b64 v[60:61], 13, v[60:61]
	v_cvt_pk_bf16_f32 v62, v52, v53
	v_pk_mul_f32 v[52:53], v[54:55], v[54:55]
	v_cvt_pk_bf16_f32 v63, v48, v49
	v_pk_mul_f32 v[48:49], v[50:51], v[50:51]
	v_max_f32_e32 v44, 0, v44
	v_max_f32_e32 v45, 0, v45
	v_max_f32_e32 v46, v46, v46
	v_max_f32_e32 v47, v47, v47
	v_max_f32_e32 v40, 0, v40
	v_max_f32_e32 v41, 0, v41
	v_max_f32_e32 v42, v42, v42
	v_max_f32_e32 v43, v43, v43
	v_cvt_pk_bf16_f32 v55, v52, v53
	v_cvt_pk_bf16_f32 v48, v48, v49
	v_lshl_add_u64 v[52:53], v[120:121], 0, v[60:61]
	v_max_f32_e32 v46, 0, v46
	v_max_f32_e32 v47, 0, v47
	v_pk_mul_f32 v[44:45], v[44:45], v[44:45]
	v_max_f32_e32 v42, 0, v42
	v_max_f32_e32 v43, 0, v43
	v_pk_mul_f32 v[40:41], v[40:41], v[40:41]
	v_cndmask_b32_e32 v49, v55, v48, vcc
	global_store_dwordx4 v[52:53], v[56:59], off
	ds_bpermute_b32 v49, v132, v49
	v_cndmask_b32_e32 v66, v69, v78, vcc
	v_cvt_pk_bf16_f32 v56, v44, v45
	v_pk_mul_f32 v[44:45], v[46:47], v[46:47]
	v_cvt_pk_bf16_f32 v57, v40, v41
	v_pk_mul_f32 v[40:41], v[42:43], v[42:43]
	v_cvt_pk_bf16_f32 v47, v44, v45
	v_cvt_pk_bf16_f32 v40, v40, v41
	v_cndmask_b32_e32 v64, v78, v77, vcc
	v_cndmask_b32_e32 v50, v62, v63, vcc
	v_cndmask_b32_e32 v41, v47, v40, vcc
	global_store_dwordx4 v[90:91], v[64:67], off offset:256
	ds_bpermute_b32 v64, v132, v50
	ds_bpermute_b32 v41, v132, v41
	v_cndmask_b32_e32 v42, v56, v57, vcc
	v_add_u32_e32 v54, 0x90, v130
	ds_bpermute_b32 v58, v132, v42
	s_waitcnt lgkmcnt(0)
	v_cndmask_b32_e32 v51, v48, v49, vcc
	v_cndmask_b32_e32 v49, v49, v55, vcc
	v_ashrrev_i32_e32 v55, 31, v54
	v_max_f32_e32 v36, v36, v36
	v_max_f32_e32 v37, v37, v37
	v_max_f32_e32 v32, v32, v32
	v_max_f32_e32 v33, v33, v33
	v_lshlrev_b64 v[54:55], 13, v[54:55]
	v_add_u32_e32 v46, 0xa0, v130
	v_max_f32_e32 v36, 0, v36
	v_max_f32_e32 v37, 0, v37
	v_max_f32_e32 v38, v38, v38
	v_max_f32_e32 v39, v39, v39
	v_max_f32_e32 v32, 0, v32
	v_max_f32_e32 v33, 0, v33
	v_max_f32_e32 v34, v34, v34
	v_max_f32_e32 v35, v35, v35
	v_cndmask_b32_e32 v50, v63, v64, vcc
	v_cndmask_b32_e32 v48, v64, v62, vcc
	v_lshl_add_u64 v[44:45], v[120:121], 0, v[54:55]
	v_cndmask_b32_e32 v43, v40, v41, vcc
	v_cndmask_b32_e32 v41, v41, v47, vcc
	v_ashrrev_i32_e32 v47, 31, v46
	v_max_f32_e32 v38, 0, v38
	v_max_f32_e32 v39, 0, v39
	v_pk_mul_f32 v[36:37], v[36:37], v[36:37]
	v_max_f32_e32 v34, 0, v34
	v_max_f32_e32 v35, 0, v35
	v_pk_mul_f32 v[32:33], v[32:33], v[32:33]
	v_max_f32_e32 v28, v28, v28
	v_max_f32_e32 v29, v29, v29
	global_store_dwordx4 v[44:45], v[48:51], off
	v_lshlrev_b64 v[46:47], 13, v[46:47]
	v_max_f32_e32 v28, 0, v28
	v_cvt_pk_bf16_f32 v48, v36, v37
	v_pk_mul_f32 v[36:37], v[38:39], v[38:39]
	v_cvt_pk_bf16_f32 v49, v32, v33
	v_pk_mul_f32 v[32:33], v[34:35], v[34:35]
	v_max_f32_e32 v29, 0, v29
	v_max_f32_e32 v30, v30, v30
	v_max_f32_e32 v31, v31, v31
	v_max_f32_e32 v24, v24, v24
	v_max_f32_e32 v25, v25, v25
	v_cndmask_b32_e32 v42, v57, v58, vcc
	v_cndmask_b32_e32 v40, v58, v56, vcc
	v_cvt_pk_bf16_f32 v39, v36, v37
	v_cvt_pk_bf16_f32 v32, v32, v33
	v_lshl_add_u64 v[36:37], v[120:121], 0, v[46:47]
	v_max_f32_e32 v30, 0, v30
	v_max_f32_e32 v31, 0, v31
	v_pk_mul_f32 v[28:29], v[28:29], v[28:29]
	v_max_f32_e32 v24, 0, v24
	v_max_f32_e32 v25, 0, v25
	v_max_f32_e32 v26, v26, v26
	v_max_f32_e32 v27, v27, v27
	v_cndmask_b32_e32 v33, v39, v32, vcc
	global_store_dwordx4 v[36:37], v[40:43], off
	v_max_f32_e32 v26, 0, v26
	v_max_f32_e32 v27, 0, v27
	v_cvt_pk_bf16_f32 v40, v28, v29
	v_pk_mul_f32 v[28:29], v[30:31], v[30:31]
	v_pk_mul_f32 v[24:25], v[24:25], v[24:25]
	ds_bpermute_b32 v33, v132, v33
	v_cvt_pk_bf16_f32 v28, v28, v29
	v_cvt_pk_bf16_f32 v29, v24, v25
	v_pk_mul_f32 v[24:25], v[26:27], v[26:27]
	v_add_u32_e32 v38, 0xb0, v130
	v_cvt_pk_bf16_f32 v30, v24, v25
	v_cndmask_b32_e32 v25, v40, v29, vcc
	ds_bpermute_b32 v41, v132, v25
	v_max_f32_e32 v20, v20, v20
	v_max_f32_e32 v21, v21, v21
	s_waitcnt lgkmcnt(0)
	v_cndmask_b32_e32 v35, v32, v33, vcc
	v_cndmask_b32_e32 v33, v33, v39, vcc
	v_ashrrev_i32_e32 v39, 31, v38
	v_cndmask_b32_e32 v24, v28, v30, vcc
	v_max_f32_e32 v20, 0, v20
	v_max_f32_e32 v21, 0, v21
	v_max_f32_e32 v22, v22, v22
	v_max_f32_e32 v23, v23, v23
	v_max_f32_e32 v16, v16, v16
	v_max_f32_e32 v17, v17, v17
	ds_bpermute_b32 v31, v132, v24
	v_lshlrev_b64 v[24:25], 13, v[38:39]
	v_max_f32_e32 v22, 0, v22
	v_max_f32_e32 v23, 0, v23
	v_pk_mul_f32 v[20:21], v[20:21], v[20:21]
	v_max_f32_e32 v16, 0, v16
	v_max_f32_e32 v17, 0, v17
	v_max_f32_e32 v18, v18, v18
	v_max_f32_e32 v19, v19, v19
	v_lshl_add_u64 v[26:27], v[120:121], 0, v[24:25]
	v_cndmask_b32_e32 v24, v29, v41, vcc
	v_cvt_pk_bf16_f32 v29, v20, v21
	v_pk_mul_f32 v[20:21], v[22:23], v[22:23]
	v_max_f32_e32 v18, 0, v18
	v_max_f32_e32 v19, 0, v19
	v_pk_mul_f32 v[16:17], v[16:17], v[16:17]
	v_cvt_pk_bf16_f32 v20, v20, v21
	v_cvt_pk_bf16_f32 v21, v16, v17
	v_pk_mul_f32 v[16:17], v[18:19], v[18:19]
	v_cndmask_b32_e32 v18, v29, v21, vcc
	v_cvt_pk_bf16_f32 v16, v16, v17
	v_cndmask_b32_e32 v17, v20, v16, vcc
	ds_bpermute_b32 v19, v132, v17
	ds_bpermute_b32 v18, v132, v18
	v_max_f32_e32 v12, v12, v12
	v_max_f32_e32 v13, v13, v13
	v_max_f32_e32 v12, 0, v12
	v_max_f32_e32 v13, 0, v13
	v_max_f32_e32 v14, v14, v14
	v_max_f32_e32 v15, v15, v15
	v_max_f32_e32 v8, v8, v8
	v_max_f32_e32 v9, v9, v9
	v_max_f32_e32 v14, 0, v14
	v_max_f32_e32 v15, 0, v15
	v_pk_mul_f32 v[12:13], v[12:13], v[12:13]
	v_max_f32_e32 v8, 0, v8
	v_max_f32_e32 v9, 0, v9
	v_max_f32_e32 v10, v10, v10
	v_max_f32_e32 v11, v11, v11
	s_waitcnt lgkmcnt(0)
	v_cndmask_b32_e32 v17, v16, v19, vcc
	v_cndmask_b32_e32 v16, v21, v18, vcc
	v_cvt_pk_bf16_f32 v21, v12, v13
	v_pk_mul_f32 v[12:13], v[14:15], v[14:15]
	v_max_f32_e32 v10, 0, v10
	v_max_f32_e32 v11, 0, v11
	v_pk_mul_f32 v[8:9], v[8:9], v[8:9]
	v_cvt_pk_bf16_f32 v12, v12, v13
	v_cvt_pk_bf16_f32 v13, v8, v9
	v_pk_mul_f32 v[8:9], v[10:11], v[10:11]
	v_cndmask_b32_e32 v10, v21, v13, vcc
	v_cvt_pk_bf16_f32 v8, v8, v9
	v_cndmask_b32_e32 v9, v12, v8, vcc
	ds_bpermute_b32 v11, v132, v9
	ds_bpermute_b32 v10, v132, v10
	v_max_f32_e32 v4, v4, v4
	v_max_f32_e32 v5, v5, v5
	v_max_f32_e32 v4, 0, v4
	v_max_f32_e32 v5, 0, v5
	v_max_f32_e32 v6, v6, v6
	v_max_f32_e32 v7, v7, v7
	v_max_f32_e32 v0, v0, v0
	v_max_f32_e32 v1, v1, v1
	v_max_f32_e32 v6, 0, v6
	v_max_f32_e32 v7, 0, v7
	v_pk_mul_f32 v[4:5], v[4:5], v[4:5]
	v_max_f32_e32 v0, 0, v0
	v_max_f32_e32 v1, 0, v1
	v_max_f32_e32 v2, v2, v2
	v_max_f32_e32 v3, v3, v3
	s_waitcnt lgkmcnt(0)
	v_cndmask_b32_e32 v9, v8, v11, vcc
	v_cndmask_b32_e32 v8, v13, v10, vcc
	v_cvt_pk_bf16_f32 v13, v4, v5
	v_pk_mul_f32 v[4:5], v[6:7], v[6:7]
	v_max_f32_e32 v2, 0, v2
	v_max_f32_e32 v3, 0, v3
	v_pk_mul_f32 v[0:1], v[0:1], v[0:1]
	v_cvt_pk_bf16_f32 v4, v4, v5
	v_cvt_pk_bf16_f32 v5, v0, v1
	v_pk_mul_f32 v[0:1], v[2:3], v[2:3]
	v_cndmask_b32_e32 v98, v112, v113, vcc
	v_cvt_pk_bf16_f32 v0, v0, v1
	v_cndmask_b32_e32 v34, v48, v49, vcc
	v_cndmask_b32_e32 v15, v19, v20, vcc
	v_cndmask_b32_e32 v14, v18, v29, vcc
	v_cndmask_b32_e32 v1, v4, v0, vcc
	v_cndmask_b32_e32 v2, v13, v5, vcc
	ds_bpermute_b32 v114, v132, v98
	ds_bpermute_b32 v50, v132, v34
	global_store_dwordx4 v[44:45], v[14:17], off offset:256
	ds_bpermute_b32 v1, v132, v1
	ds_bpermute_b32 v14, v132, v2
	s_lshr_b32 s0, s90, 3
	s_waitcnt lgkmcnt(0)
	v_cndmask_b32_e32 v98, v113, v114, vcc
	v_cndmask_b32_e32 v96, v114, v112, vcc
	v_cndmask_b32_e32 v89, v94, v95, vcc
	v_cndmask_b32_e32 v87, v95, v92, vcc
	v_cndmask_b32_e32 v86, v105, v104, vcc
	v_cndmask_b32_e32 v71, v75, v76, vcc
	v_cndmask_b32_e32 v70, v74, v85, vcc
	v_cndmask_b32_e32 v34, v49, v50, vcc
	v_cndmask_b32_e32 v32, v50, v48, vcc
	v_cndmask_b32_e32 v25, v30, v31, vcc
	v_cndmask_b32_e32 v23, v31, v28, vcc
	v_cndmask_b32_e32 v22, v41, v40, vcc
	v_cndmask_b32_e32 v7, v11, v12, vcc
	v_cndmask_b32_e32 v6, v10, v21, vcc
	v_cndmask_b32_e32 v3, v0, v1, vcc
	v_cndmask_b32_e32 v2, v5, v14, vcc
	v_cndmask_b32_e32 v1, v1, v4, vcc
	v_cndmask_b32_e32 v0, v14, v13, vcc
	s_add_i32 s38, s38, s0
	s_and_b64 vcc, exec, s[58:59]
	global_store_dwordx4 v[90:91], v[96:99], off
	global_store_dwordx4 v[116:117], v[86:89], off offset:256
	global_store_dwordx4 v[100:101], v[70:73], off offset:256
	global_store_dwordx4 v[26:27], v[32:35], off
	global_store_dwordx4 v[52:53], v[22:25], off offset:256
	global_store_dwordx4 v[36:37], v[6:9], off offset:256
	global_store_dwordx4 v[26:27], v[0:3], off offset:256
	s_waitcnt vmcnt(0)
	s_barrier
	s_cbranch_vccnz .LBB0_1666

.LBB0_1657:
	s_barrier
	s_setprio 1
	s_or_b64 exec, exec, s[60:61]
	s_mov_b64 s[60:61], -1
	s_and_b64 vcc, exec, s[58:59]
	s_cbranch_vccnz .LBB0_1655

.LBB0_2906:
	s_setprio 0
	s_or_b64 exec, exec, s[44:45]
	v_and_b32_e32 v134, 64, v165
	v_xor_b32_e32 v132, 16, v165
	v_add_u32_e32 v134, 64, v134
	v_max_f32_e32 v124, v124, v124
	v_max_f32_e32 v125, v125, v125
	v_and_b32_e32 v128, 16, v128
	v_lshlrev_b32_e32 v133, 2, v155
	v_cmp_lt_i32_e32 vcc, v132, v134
	v_max_f32_e32 v124, 0, v124
	v_max_f32_e32 v125, 0, v125
	v_max_f32_e32 v126, v126, v126
	v_max_f32_e32 v127, v127, v127
	v_max_f32_e32 v120, v120, v120
	v_max_f32_e32 v121, v121, v121
	v_cndmask_b32_e32 v132, v165, v132, vcc
	v_add_u32_e32 v134, 12, v133
	v_cmp_eq_u32_e32 vcc, 0, v128
	v_max_f32_e32 v126, 0, v126
	v_max_f32_e32 v127, 0, v127
	v_pk_mul_f32 v[124:125], v[124:125], v[124:125]
	v_max_f32_e32 v120, 0, v120
	v_max_f32_e32 v121, 0, v121
	v_max_f32_e32 v122, v122, v122
	v_max_f32_e32 v123, v123, v123
	v_cndmask_b32_e32 v128, v134, v133, vcc
	v_cvt_pk_bf16_f32 v133, v124, v125
	v_pk_mul_f32 v[124:125], v[126:127], v[126:127]
	v_max_f32_e32 v122, 0, v122
	v_max_f32_e32 v123, 0, v123
	v_pk_mul_f32 v[120:121], v[120:121], v[120:121]
	v_cvt_pk_bf16_f32 v126, v124, v125
	v_cvt_pk_bf16_f32 v124, v120, v121
	v_pk_mul_f32 v[120:121], v[122:123], v[122:123]
	v_lshlrev_b32_e32 v132, 2, v132
	v_cvt_pk_bf16_f32 v122, v120, v121
	v_cndmask_b32_e32 v120, v126, v122, vcc
	v_cndmask_b32_e32 v121, v133, v124, vcc
	ds_bpermute_b32 v123, v132, v120
	ds_bpermute_b32 v127, v132, v121
	s_lshl_b32 s4, s61, 8
	v_or_b32_e32 v130, s36, v156
	v_lshlrev_b32_e32 v131, 5, v154
	v_max_f32_e32 v116, v116, v116
	v_max_f32_e32 v117, v117, v117
	v_max_f32_e32 v112, v112, v112
	v_max_f32_e32 v113, v113, v113
	v_add_u32_e32 v130, v130, v157
	v_or3_b32 v120, v131, s4, v128
	v_max_f32_e32 v116, 0, v116
	v_max_f32_e32 v117, 0, v117
	v_max_f32_e32 v118, v118, v118
	v_max_f32_e32 v119, v119, v119
	v_max_f32_e32 v112, 0, v112
	v_max_f32_e32 v113, 0, v113
	v_max_f32_e32 v114, v114, v114
	v_max_f32_e32 v115, v115, v115
	v_lshlrev_b32_e32 v128, 1, v120
	v_ashrrev_i32_e32 v131, 31, v130
	v_max_f32_e32 v118, 0, v118
	v_max_f32_e32 v119, 0, v119
	v_pk_mul_f32 v[116:117], v[116:117], v[116:117]
	v_max_f32_e32 v114, 0, v114
	v_max_f32_e32 v115, 0, v115
	v_pk_mul_f32 v[112:113], v[112:113], v[112:113]
	v_max_f32_e32 v108, v108, v108
	v_max_f32_e32 v109, v109, v109
	v_max_f32_e32 v104, v104, v104
	v_max_f32_e32 v105, v105, v105
	v_lshl_add_u64 v[120:121], s[8:9], 0, v[128:129]
	s_waitcnt lgkmcnt(0)
	v_cndmask_b32_e32 v125, v122, v123, vcc
	v_cndmask_b32_e32 v124, v124, v127, vcc
	v_cndmask_b32_e32 v123, v123, v126, vcc
	v_cndmask_b32_e32 v122, v127, v133, vcc
	v_lshlrev_b64 v[126:127], 13, v[130:131]
	v_cvt_pk_bf16_f32 v128, v116, v117
	v_pk_mul_f32 v[116:117], v[118:119], v[118:119]
	v_cvt_pk_bf16_f32 v131, v112, v113
	v_pk_mul_f32 v[112:113], v[114:115], v[114:115]
	v_max_f32_e32 v108, 0, v108
	v_max_f32_e32 v109, 0, v109
	v_max_f32_e32 v110, v110, v110
	v_max_f32_e32 v111, v111, v111
	v_max_f32_e32 v104, 0, v104
	v_max_f32_e32 v105, 0, v105
	v_max_f32_e32 v106, v106, v106
	v_max_f32_e32 v107, v107, v107
	v_cvt_pk_bf16_f32 v119, v116, v117
	v_cvt_pk_bf16_f32 v112, v112, v113
	v_lshl_add_u64 v[116:117], v[120:121], 0, v[126:127]
	v_max_f32_e32 v110, 0, v110
	v_max_f32_e32 v111, 0, v111
	v_pk_mul_f32 v[108:109], v[108:109], v[108:109]
	v_max_f32_e32 v106, 0, v106
	v_max_f32_e32 v107, 0, v107
	v_pk_mul_f32 v[104:105], v[104:105], v[104:105]
	v_cndmask_b32_e32 v113, v119, v112, vcc
	global_store_dwordx4 v[116:117], v[122:125], off
	ds_bpermute_b32 v113, v132, v113
	v_cndmask_b32_e32 v114, v128, v131, vcc
	v_cvt_pk_bf16_f32 v122, v108, v109
	v_pk_mul_f32 v[108:109], v[110:111], v[110:111]
	v_cvt_pk_bf16_f32 v123, v104, v105
	v_pk_mul_f32 v[104:105], v[106:107], v[106:107]
	v_cvt_pk_bf16_f32 v111, v108, v109
	v_cvt_pk_bf16_f32 v104, v104, v105
	v_cndmask_b32_e32 v105, v111, v104, vcc
	ds_bpermute_b32 v133, v132, v114
	ds_bpermute_b32 v105, v132, v105
	v_cndmask_b32_e32 v106, v122, v123, vcc
	v_or_b32_e32 v118, 16, v130
	ds_bpermute_b32 v124, v132, v106
	s_waitcnt lgkmcnt(0)
	v_cndmask_b32_e32 v115, v112, v113, vcc
	v_cndmask_b32_e32 v113, v113, v119, vcc
	v_ashrrev_i32_e32 v119, 31, v118
	v_max_f32_e32 v100, v100, v100
	v_max_f32_e32 v101, v101, v101
	v_max_f32_e32 v96, v96, v96
	v_max_f32_e32 v97, v97, v97
	v_lshlrev_b64 v[118:119], 13, v[118:119]
	v_or_b32_e32 v110, 32, v130
	v_max_f32_e32 v100, 0, v100
	v_max_f32_e32 v101, 0, v101
	v_max_f32_e32 v102, v102, v102
	v_max_f32_e32 v103, v103, v103
	v_max_f32_e32 v96, 0, v96
	v_max_f32_e32 v97, 0, v97
	v_max_f32_e32 v98, v98, v98
	v_max_f32_e32 v99, v99, v99
	v_cndmask_b32_e32 v114, v131, v133, vcc
	v_cndmask_b32_e32 v112, v133, v128, vcc
	v_lshl_add_u64 v[108:109], v[120:121], 0, v[118:119]
	v_cndmask_b32_e32 v107, v104, v105, vcc
	v_cndmask_b32_e32 v105, v105, v111, vcc
	v_ashrrev_i32_e32 v111, 31, v110
	v_max_f32_e32 v102, 0, v102
	v_max_f32_e32 v103, 0, v103
	v_pk_mul_f32 v[100:101], v[100:101], v[100:101]
	v_max_f32_e32 v98, 0, v98
	v_max_f32_e32 v99, 0, v99
	v_pk_mul_f32 v[96:97], v[96:97], v[96:97]
	v_max_f32_e32 v92, v92, v92
	v_max_f32_e32 v93, v93, v93
	global_store_dwordx4 v[108:109], v[112:115], off
	v_lshlrev_b64 v[110:111], 13, v[110:111]
	v_max_f32_e32 v92, 0, v92
	v_cvt_pk_bf16_f32 v112, v100, v101
	v_pk_mul_f32 v[100:101], v[102:103], v[102:103]
	v_cvt_pk_bf16_f32 v113, v96, v97
	v_pk_mul_f32 v[96:97], v[98:99], v[98:99]
	v_max_f32_e32 v93, 0, v93
	v_max_f32_e32 v94, v94, v94
	v_max_f32_e32 v95, v95, v95
	v_max_f32_e32 v88, v88, v88
	v_max_f32_e32 v89, v89, v89
	v_cndmask_b32_e32 v106, v123, v124, vcc
	v_cndmask_b32_e32 v104, v124, v122, vcc
	v_cvt_pk_bf16_f32 v103, v100, v101
	v_cvt_pk_bf16_f32 v96, v96, v97
	v_lshl_add_u64 v[100:101], v[120:121], 0, v[110:111]
	v_max_f32_e32 v94, 0, v94
	v_max_f32_e32 v95, 0, v95
	v_pk_mul_f32 v[92:93], v[92:93], v[92:93]
	v_max_f32_e32 v88, 0, v88
	v_max_f32_e32 v89, 0, v89
	v_max_f32_e32 v90, v90, v90
	v_max_f32_e32 v91, v91, v91
	v_cndmask_b32_e32 v97, v103, v96, vcc
	global_store_dwordx4 v[100:101], v[104:107], off
	v_max_f32_e32 v90, 0, v90
	v_max_f32_e32 v91, 0, v91
	v_cvt_pk_bf16_f32 v104, v92, v93
	v_pk_mul_f32 v[92:93], v[94:95], v[94:95]
	v_pk_mul_f32 v[88:89], v[88:89], v[88:89]
	ds_bpermute_b32 v97, v132, v97
	v_cvt_pk_bf16_f32 v92, v92, v93
	v_cvt_pk_bf16_f32 v93, v88, v89
	v_pk_mul_f32 v[88:89], v[90:91], v[90:91]
	v_or_b32_e32 v102, 48, v130
	v_cvt_pk_bf16_f32 v94, v88, v89
	v_cndmask_b32_e32 v89, v104, v93, vcc
	ds_bpermute_b32 v105, v132, v89
	v_max_f32_e32 v84, v84, v84
	v_max_f32_e32 v85, v85, v85
	s_waitcnt lgkmcnt(0)
	v_cndmask_b32_e32 v99, v96, v97, vcc
	v_cndmask_b32_e32 v97, v97, v103, vcc
	v_ashrrev_i32_e32 v103, 31, v102
	v_cndmask_b32_e32 v88, v92, v94, vcc
	v_max_f32_e32 v84, 0, v84
	v_max_f32_e32 v85, 0, v85
	v_max_f32_e32 v86, v86, v86
	v_max_f32_e32 v87, v87, v87
	v_max_f32_e32 v80, v80, v80
	v_max_f32_e32 v81, v81, v81
	ds_bpermute_b32 v95, v132, v88
	v_lshlrev_b64 v[88:89], 13, v[102:103]
	v_max_f32_e32 v86, 0, v86
	v_max_f32_e32 v87, 0, v87
	v_pk_mul_f32 v[84:85], v[84:85], v[84:85]
	v_max_f32_e32 v80, 0, v80
	v_max_f32_e32 v81, 0, v81
	v_max_f32_e32 v82, v82, v82
	v_max_f32_e32 v83, v83, v83
	v_lshl_add_u64 v[90:91], v[120:121], 0, v[88:89]
	v_cndmask_b32_e32 v88, v93, v105, vcc
	v_cvt_pk_bf16_f32 v93, v84, v85
	v_pk_mul_f32 v[84:85], v[86:87], v[86:87]
	v_max_f32_e32 v82, 0, v82
	v_max_f32_e32 v83, 0, v83
	v_pk_mul_f32 v[80:81], v[80:81], v[80:81]
	v_cvt_pk_bf16_f32 v84, v84, v85
	v_cvt_pk_bf16_f32 v85, v80, v81
	v_pk_mul_f32 v[80:81], v[82:83], v[82:83]
	v_cndmask_b32_e32 v82, v93, v85, vcc
	v_cvt_pk_bf16_f32 v80, v80, v81
	v_cndmask_b32_e32 v81, v84, v80, vcc
	ds_bpermute_b32 v83, v132, v81
	ds_bpermute_b32 v82, v132, v82
	v_max_f32_e32 v76, v76, v76
	v_max_f32_e32 v77, v77, v77
	v_max_f32_e32 v76, 0, v76
	v_max_f32_e32 v77, 0, v77
	v_max_f32_e32 v78, v78, v78
	v_max_f32_e32 v79, v79, v79
	v_max_f32_e32 v72, v72, v72
	v_max_f32_e32 v73, v73, v73
	v_max_f32_e32 v78, 0, v78
	v_max_f32_e32 v79, 0, v79
	v_pk_mul_f32 v[76:77], v[76:77], v[76:77]
	v_max_f32_e32 v72, 0, v72
	v_max_f32_e32 v73, 0, v73
	v_max_f32_e32 v74, v74, v74
	v_max_f32_e32 v75, v75, v75
	s_waitcnt lgkmcnt(0)
	v_cndmask_b32_e32 v81, v80, v83, vcc
	v_cndmask_b32_e32 v80, v85, v82, vcc
	v_cvt_pk_bf16_f32 v85, v76, v77
	v_pk_mul_f32 v[76:77], v[78:79], v[78:79]
	v_max_f32_e32 v74, 0, v74
	v_max_f32_e32 v75, 0, v75
	v_pk_mul_f32 v[72:73], v[72:73], v[72:73]
	v_cvt_pk_bf16_f32 v76, v76, v77
	v_cvt_pk_bf16_f32 v77, v72, v73
	v_pk_mul_f32 v[72:73], v[74:75], v[74:75]
	v_cndmask_b32_e32 v74, v85, v77, vcc
	v_cvt_pk_bf16_f32 v72, v72, v73
	v_cndmask_b32_e32 v73, v76, v72, vcc
	ds_bpermute_b32 v75, v132, v73
	ds_bpermute_b32 v74, v132, v74
	v_max_f32_e32 v68, v68, v68
	v_max_f32_e32 v69, v69, v69
	v_max_f32_e32 v68, 0, v68
	v_max_f32_e32 v69, 0, v69
	v_max_f32_e32 v70, v70, v70
	v_max_f32_e32 v71, v71, v71
	v_max_f32_e32 v64, v64, v64
	v_max_f32_e32 v65, v65, v65
	v_max_f32_e32 v70, 0, v70
	v_max_f32_e32 v71, 0, v71
	v_pk_mul_f32 v[68:69], v[68:69], v[68:69]
	v_max_f32_e32 v64, 0, v64
	v_max_f32_e32 v65, 0, v65
	v_max_f32_e32 v66, v66, v66
	v_max_f32_e32 v67, v67, v67
	s_waitcnt lgkmcnt(0)
	v_cndmask_b32_e32 v73, v72, v75, vcc
	v_cndmask_b32_e32 v72, v77, v74, vcc
	v_cvt_pk_bf16_f32 v77, v68, v69
	v_pk_mul_f32 v[68:69], v[70:71], v[70:71]
	v_max_f32_e32 v66, 0, v66
	v_max_f32_e32 v67, 0, v67
	v_pk_mul_f32 v[64:65], v[64:65], v[64:65]
	v_cvt_pk_bf16_f32 v68, v68, v69
	v_cvt_pk_bf16_f32 v69, v64, v65
	v_pk_mul_f32 v[64:65], v[66:67], v[66:67]
	v_max_f32_e32 v60, v60, v60
	v_cvt_pk_bf16_f32 v64, v64, v65
	v_cndmask_b32_e32 v65, v68, v64, vcc
	ds_bpermute_b32 v65, v132, v65
	v_max_f32_e32 v61, v61, v61
	v_max_f32_e32 v56, v56, v56
	v_max_f32_e32 v57, v57, v57
	v_max_f32_e32 v60, 0, v60
	v_max_f32_e32 v61, 0, v61
	v_max_f32_e32 v62, v62, v62
	v_max_f32_e32 v63, v63, v63
	v_max_f32_e32 v56, 0, v56
	v_max_f32_e32 v57, 0, v57
	v_max_f32_e32 v58, v58, v58
	v_max_f32_e32 v59, v59, v59
	v_max_f32_e32 v62, 0, v62
	v_max_f32_e32 v63, 0, v63
	v_pk_mul_f32 v[60:61], v[60:61], v[60:61]
	v_max_f32_e32 v58, 0, v58
	v_max_f32_e32 v59, 0, v59
	v_pk_mul_f32 v[56:57], v[56:57], v[56:57]
	s_waitcnt lgkmcnt(0)
	v_cndmask_b32_e32 v67, v64, v65, vcc
	v_cndmask_b32_e32 v65, v65, v68, vcc
	v_cvt_pk_bf16_f32 v68, v60, v61
	v_pk_mul_f32 v[60:61], v[62:63], v[62:63]
	v_cvt_pk_bf16_f32 v62, v56, v57
	v_pk_mul_f32 v[56:57], v[58:59], v[58:59]
	v_cvt_pk_bf16_f32 v61, v60, v61
	v_cvt_pk_bf16_f32 v56, v56, v57
	v_cndmask_b32_e32 v57, v61, v56, vcc
	v_cndmask_b32_e32 v58, v68, v62, vcc
	ds_bpermute_b32 v57, v132, v57
	ds_bpermute_b32 v63, v132, v58
	v_max_f32_e32 v52, v52, v52
	v_max_f32_e32 v53, v53, v53
	v_max_f32_e32 v48, v48, v48
	v_max_f32_e32 v49, v49, v49
	v_cndmask_b32_e32 v79, v83, v84, vcc
	v_cndmask_b32_e32 v78, v82, v93, vcc
	v_cndmask_b32_e32 v66, v77, v69, vcc
	v_add_u32_e32 v60, 0x80, v130
	v_max_f32_e32 v52, 0, v52
	v_max_f32_e32 v53, 0, v53
	v_max_f32_e32 v54, v54, v54
	v_max_f32_e32 v55, v55, v55
	v_max_f32_e32 v48, 0, v48
	v_max_f32_e32 v49, 0, v49
	v_max_f32_e32 v50, v50, v50
	v_max_f32_e32 v51, v51, v51
	global_store_dwordx4 v[108:109], v[78:81], off offset:256
	ds_bpermute_b32 v78, v132, v66
	s_waitcnt lgkmcnt(0)
	v_cndmask_b32_e32 v59, v56, v57, vcc
	v_cndmask_b32_e32 v57, v57, v61, vcc
	v_ashrrev_i32_e32 v61, 31, v60
	v_max_f32_e32 v54, 0, v54
	v_max_f32_e32 v55, 0, v55
	v_pk_mul_f32 v[52:53], v[52:53], v[52:53]
	v_max_f32_e32 v50, 0, v50
	v_max_f32_e32 v51, 0, v51
	v_pk_mul_f32 v[48:49], v[48:49], v[48:49]
	v_max_f32_e32 v44, v44, v44
	v_max_f32_e32 v45, v45, v45
	v_max_f32_e32 v40, v40, v40
	v_max_f32_e32 v41, v41, v41
	v_cndmask_b32_e32 v58, v62, v63, vcc
	v_cndmask_b32_e32 v56, v63, v68, vcc
	v_lshlrev_b64 v[60:61], 13, v[60:61]
	v_cvt_pk_bf16_f32 v62, v52, v53
	v_pk_mul_f32 v[52:53], v[54:55], v[54:55]
	v_cvt_pk_bf16_f32 v63, v48, v49
	v_pk_mul_f32 v[48:49], v[50:51], v[50:51]
	v_max_f32_e32 v44, 0, v44
	v_max_f32_e32 v45, 0, v45
	v_max_f32_e32 v46, v46, v46
	v_max_f32_e32 v47, v47, v47
	v_max_f32_e32 v40, 0, v40
	v_max_f32_e32 v41, 0, v41
	v_max_f32_e32 v42, v42, v42
	v_max_f32_e32 v43, v43, v43
	v_cvt_pk_bf16_f32 v55, v52, v53
	v_cvt_pk_bf16_f32 v48, v48, v49
	v_lshl_add_u64 v[52:53], v[120:121], 0, v[60:61]
	v_max_f32_e32 v46, 0, v46
	v_max_f32_e32 v47, 0, v47
	v_pk_mul_f32 v[44:45], v[44:45], v[44:45]
	v_max_f32_e32 v42, 0, v42
	v_max_f32_e32 v43, 0, v43
	v_pk_mul_f32 v[40:41], v[40:41], v[40:41]
	v_cndmask_b32_e32 v49, v55, v48, vcc
	global_store_dwordx4 v[52:53], v[56:59], off
	ds_bpermute_b32 v49, v132, v49
	v_cndmask_b32_e32 v66, v69, v78, vcc
	v_cvt_pk_bf16_f32 v56, v44, v45
	v_pk_mul_f32 v[44:45], v[46:47], v[46:47]
	v_cvt_pk_bf16_f32 v57, v40, v41
	v_pk_mul_f32 v[40:41], v[42:43], v[42:43]
	v_cvt_pk_bf16_f32 v47, v44, v45
	v_cvt_pk_bf16_f32 v40, v40, v41
	v_cndmask_b32_e32 v64, v78, v77, vcc
	v_cndmask_b32_e32 v50, v62, v63, vcc
	v_cndmask_b32_e32 v41, v47, v40, vcc
	global_store_dwordx4 v[90:91], v[64:67], off offset:256
	ds_bpermute_b32 v64, v132, v50
	ds_bpermute_b32 v41, v132, v41
	v_cndmask_b32_e32 v42, v56, v57, vcc
	v_add_u32_e32 v54, 0x90, v130
	ds_bpermute_b32 v58, v132, v42
	s_waitcnt lgkmcnt(0)
	v_cndmask_b32_e32 v51, v48, v49, vcc
	v_cndmask_b32_e32 v49, v49, v55, vcc
	v_ashrrev_i32_e32 v55, 31, v54
	v_max_f32_e32 v36, v36, v36
	v_max_f32_e32 v37, v37, v37
	v_max_f32_e32 v32, v32, v32
	v_max_f32_e32 v33, v33, v33
	v_lshlrev_b64 v[54:55], 13, v[54:55]
	v_add_u32_e32 v46, 0xa0, v130
	v_max_f32_e32 v36, 0, v36
	v_max_f32_e32 v37, 0, v37
	v_max_f32_e32 v38, v38, v38
	v_max_f32_e32 v39, v39, v39
	v_max_f32_e32 v32, 0, v32
	v_max_f32_e32 v33, 0, v33
	v_max_f32_e32 v34, v34, v34
	v_max_f32_e32 v35, v35, v35
	v_cndmask_b32_e32 v50, v63, v64, vcc
	v_cndmask_b32_e32 v48, v64, v62, vcc
	v_lshl_add_u64 v[44:45], v[120:121], 0, v[54:55]
	v_cndmask_b32_e32 v43, v40, v41, vcc
	v_cndmask_b32_e32 v41, v41, v47, vcc
	v_ashrrev_i32_e32 v47, 31, v46
	v_max_f32_e32 v38, 0, v38
	v_max_f32_e32 v39, 0, v39
	v_pk_mul_f32 v[36:37], v[36:37], v[36:37]
	v_max_f32_e32 v34, 0, v34
	v_max_f32_e32 v35, 0, v35
	v_pk_mul_f32 v[32:33], v[32:33], v[32:33]
	v_max_f32_e32 v28, v28, v28
	v_max_f32_e32 v29, v29, v29
	global_store_dwordx4 v[44:45], v[48:51], off
	v_lshlrev_b64 v[46:47], 13, v[46:47]
	v_max_f32_e32 v28, 0, v28
	v_cvt_pk_bf16_f32 v48, v36, v37
	v_pk_mul_f32 v[36:37], v[38:39], v[38:39]
	v_cvt_pk_bf16_f32 v49, v32, v33
	v_pk_mul_f32 v[32:33], v[34:35], v[34:35]
	v_max_f32_e32 v29, 0, v29
	v_max_f32_e32 v30, v30, v30
	v_max_f32_e32 v31, v31, v31
	v_max_f32_e32 v24, v24, v24
	v_max_f32_e32 v25, v25, v25
	v_cndmask_b32_e32 v42, v57, v58, vcc
	v_cndmask_b32_e32 v40, v58, v56, vcc
	v_cvt_pk_bf16_f32 v39, v36, v37
	v_cvt_pk_bf16_f32 v32, v32, v33
	v_lshl_add_u64 v[36:37], v[120:121], 0, v[46:47]
	v_max_f32_e32 v30, 0, v30
	v_max_f32_e32 v31, 0, v31
	v_pk_mul_f32 v[28:29], v[28:29], v[28:29]
	v_max_f32_e32 v24, 0, v24
	v_max_f32_e32 v25, 0, v25
	v_max_f32_e32 v26, v26, v26
	v_max_f32_e32 v27, v27, v27
	v_cndmask_b32_e32 v33, v39, v32, vcc
	global_store_dwordx4 v[36:37], v[40:43], off
	v_max_f32_e32 v26, 0, v26
	v_max_f32_e32 v27, 0, v27
	v_cvt_pk_bf16_f32 v40, v28, v29
	v_pk_mul_f32 v[28:29], v[30:31], v[30:31]
	v_pk_mul_f32 v[24:25], v[24:25], v[24:25]
	ds_bpermute_b32 v33, v132, v33
	v_cvt_pk_bf16_f32 v28, v28, v29
	v_cvt_pk_bf16_f32 v29, v24, v25
	v_pk_mul_f32 v[24:25], v[26:27], v[26:27]
	v_add_u32_e32 v38, 0xb0, v130
	v_cvt_pk_bf16_f32 v30, v24, v25
	v_cndmask_b32_e32 v25, v40, v29, vcc
	ds_bpermute_b32 v41, v132, v25
	v_max_f32_e32 v20, v20, v20
	v_max_f32_e32 v21, v21, v21
	s_waitcnt lgkmcnt(0)
	v_cndmask_b32_e32 v35, v32, v33, vcc
	v_cndmask_b32_e32 v33, v33, v39, vcc
	v_ashrrev_i32_e32 v39, 31, v38
	v_cndmask_b32_e32 v24, v28, v30, vcc
	v_max_f32_e32 v20, 0, v20
	v_max_f32_e32 v21, 0, v21
	v_max_f32_e32 v22, v22, v22
	v_max_f32_e32 v23, v23, v23
	v_max_f32_e32 v16, v16, v16
	v_max_f32_e32 v17, v17, v17
	ds_bpermute_b32 v31, v132, v24
	v_lshlrev_b64 v[24:25], 13, v[38:39]
	v_max_f32_e32 v22, 0, v22
	v_max_f32_e32 v23, 0, v23
	v_pk_mul_f32 v[20:21], v[20:21], v[20:21]
	v_max_f32_e32 v16, 0, v16
	v_max_f32_e32 v17, 0, v17
	v_max_f32_e32 v18, v18, v18
	v_max_f32_e32 v19, v19, v19
	v_lshl_add_u64 v[26:27], v[120:121], 0, v[24:25]
	v_cndmask_b32_e32 v24, v29, v41, vcc
	v_cvt_pk_bf16_f32 v29, v20, v21
	v_pk_mul_f32 v[20:21], v[22:23], v[22:23]
	v_max_f32_e32 v18, 0, v18
	v_max_f32_e32 v19, 0, v19
	v_pk_mul_f32 v[16:17], v[16:17], v[16:17]
	v_cvt_pk_bf16_f32 v20, v20, v21
	v_cvt_pk_bf16_f32 v21, v16, v17
	v_pk_mul_f32 v[16:17], v[18:19], v[18:19]
	v_cndmask_b32_e32 v18, v29, v21, vcc
	v_cvt_pk_bf16_f32 v16, v16, v17
	v_cndmask_b32_e32 v17, v20, v16, vcc
	ds_bpermute_b32 v19, v132, v17
	ds_bpermute_b32 v18, v132, v18
	v_max_f32_e32 v12, v12, v12
	v_max_f32_e32 v13, v13, v13
	v_max_f32_e32 v12, 0, v12
	v_max_f32_e32 v13, 0, v13
	v_max_f32_e32 v14, v14, v14
	v_max_f32_e32 v15, v15, v15
	v_max_f32_e32 v8, v8, v8
	v_max_f32_e32 v9, v9, v9
	v_max_f32_e32 v14, 0, v14
	v_max_f32_e32 v15, 0, v15
	v_pk_mul_f32 v[12:13], v[12:13], v[12:13]
	v_max_f32_e32 v8, 0, v8
	v_max_f32_e32 v9, 0, v9
	v_max_f32_e32 v10, v10, v10
	v_max_f32_e32 v11, v11, v11
	s_waitcnt lgkmcnt(0)
	v_cndmask_b32_e32 v17, v16, v19, vcc
	v_cndmask_b32_e32 v16, v21, v18, vcc
	v_cvt_pk_bf16_f32 v21, v12, v13
	v_pk_mul_f32 v[12:13], v[14:15], v[14:15]
	v_max_f32_e32 v10, 0, v10
	v_max_f32_e32 v11, 0, v11
	v_pk_mul_f32 v[8:9], v[8:9], v[8:9]
	v_cvt_pk_bf16_f32 v12, v12, v13
	v_cvt_pk_bf16_f32 v13, v8, v9
	v_pk_mul_f32 v[8:9], v[10:11], v[10:11]
	v_cndmask_b32_e32 v10, v21, v13, vcc
	v_cvt_pk_bf16_f32 v8, v8, v9
	v_cndmask_b32_e32 v9, v12, v8, vcc
	ds_bpermute_b32 v11, v132, v9
	ds_bpermute_b32 v10, v132, v10
	v_max_f32_e32 v4, v4, v4
	v_max_f32_e32 v5, v5, v5
	v_max_f32_e32 v4, 0, v4
	v_max_f32_e32 v5, 0, v5
	v_max_f32_e32 v6, v6, v6
	v_max_f32_e32 v7, v7, v7
	v_max_f32_e32 v0, v0, v0
	v_max_f32_e32 v1, v1, v1
	v_max_f32_e32 v6, 0, v6
	v_max_f32_e32 v7, 0, v7
	v_pk_mul_f32 v[4:5], v[4:5], v[4:5]
	v_max_f32_e32 v0, 0, v0
	v_max_f32_e32 v1, 0, v1
	v_max_f32_e32 v2, v2, v2
	v_max_f32_e32 v3, v3, v3
	s_waitcnt lgkmcnt(0)
	v_cndmask_b32_e32 v9, v8, v11, vcc
	v_cndmask_b32_e32 v8, v13, v10, vcc
	v_cvt_pk_bf16_f32 v13, v4, v5
	v_pk_mul_f32 v[4:5], v[6:7], v[6:7]
	v_max_f32_e32 v2, 0, v2
	v_max_f32_e32 v3, 0, v3
	v_pk_mul_f32 v[0:1], v[0:1], v[0:1]
	v_cvt_pk_bf16_f32 v4, v4, v5
	v_cvt_pk_bf16_f32 v5, v0, v1
	v_pk_mul_f32 v[0:1], v[2:3], v[2:3]
	v_cndmask_b32_e32 v98, v112, v113, vcc
	v_cvt_pk_bf16_f32 v0, v0, v1
	v_cndmask_b32_e32 v34, v48, v49, vcc
	v_cndmask_b32_e32 v15, v19, v20, vcc
	v_cndmask_b32_e32 v14, v18, v29, vcc
	v_cndmask_b32_e32 v1, v4, v0, vcc
	v_cndmask_b32_e32 v2, v13, v5, vcc
	ds_bpermute_b32 v114, v132, v98
	ds_bpermute_b32 v50, v132, v34
	global_store_dwordx4 v[44:45], v[14:17], off offset:256
	ds_bpermute_b32 v1, v132, v1
	ds_bpermute_b32 v14, v132, v2
	s_lshr_b32 s2, s90, 3
	s_waitcnt lgkmcnt(0)
	v_cndmask_b32_e32 v98, v113, v114, vcc
	v_cndmask_b32_e32 v96, v114, v112, vcc
	v_cndmask_b32_e32 v89, v94, v95, vcc
	v_cndmask_b32_e32 v87, v95, v92, vcc
	v_cndmask_b32_e32 v86, v105, v104, vcc
	v_cndmask_b32_e32 v71, v75, v76, vcc
	v_cndmask_b32_e32 v70, v74, v85, vcc
	v_cndmask_b32_e32 v34, v49, v50, vcc
	v_cndmask_b32_e32 v32, v50, v48, vcc
	v_cndmask_b32_e32 v25, v30, v31, vcc
	v_cndmask_b32_e32 v23, v31, v28, vcc
	v_cndmask_b32_e32 v22, v41, v40, vcc
	v_cndmask_b32_e32 v7, v11, v12, vcc
	v_cndmask_b32_e32 v6, v10, v21, vcc
	v_cndmask_b32_e32 v3, v0, v1, vcc
	v_cndmask_b32_e32 v2, v5, v14, vcc
	v_cndmask_b32_e32 v1, v1, v4, vcc
	v_cndmask_b32_e32 v0, v14, v13, vcc
	s_andn2_b64 vcc, exec, s[38:39]
	s_add_i32 s0, s0, s2
	global_store_dwordx4 v[90:91], v[96:99], off
	global_store_dwordx4 v[116:117], v[86:89], off offset:256
	global_store_dwordx4 v[100:101], v[70:73], off offset:256
	global_store_dwordx4 v[26:27], v[32:35], off
	global_store_dwordx4 v[52:53], v[22:25], off offset:256
	global_store_dwordx4 v[36:37], v[6:9], off offset:256
	global_store_dwordx4 v[26:27], v[0:3], off offset:256
	s_waitcnt vmcnt(0)
	s_barrier
	s_cbranch_vccz .LBB0_2921

.LBB0_2912:
	s_barrier
	s_setprio 1
	s_or_b64 exec, exec, s[44:45]
	s_mov_b64 s[44:45], -1
	s_and_b64 vcc, exec, s[38:39]
	s_cbranch_vccnz .LBB0_2910
